# static s_setprio 1 for waves 0-3 extended to the P1 and P4 K-loops as well (flips deleted in all four loops); rest as v058
# baseline (speedup 1.0000x reference)
.LBB0_122:
	s_add_u32 s0, s0, 0x80080
	s_addc_u32 s1, s1, 0
	s_add_u32 s65, s4, 0x100
	v_mov_b32_e32 v0, 0
	s_addc_u32 s67, s5, 0
	s_mov_b32 s78, -2
	v_mov_b32_e32 v1, v0
	v_mov_b32_e32 v2, v0
	v_mov_b32_e32 v3, v0
	v_mov_b32_e32 v4, v0
	v_mov_b32_e32 v5, v0
	v_mov_b32_e32 v6, v0
	v_mov_b32_e32 v7, v0
	v_mov_b32_e32 v16, v0
	v_mov_b32_e32 v17, v0
	v_mov_b32_e32 v18, v0
	v_mov_b32_e32 v19, v0
	v_mov_b32_e32 v20, v0
	v_mov_b32_e32 v21, v0
	v_mov_b32_e32 v22, v0
	v_mov_b32_e32 v23, v0
	v_mov_b32_e32 v32, v0
	v_mov_b32_e32 v33, v0
	v_mov_b32_e32 v34, v0
	v_mov_b32_e32 v35, v0
	v_mov_b32_e32 v36, v0
	v_mov_b32_e32 v37, v0
	v_mov_b32_e32 v38, v0
	v_mov_b32_e32 v39, v0
	v_mov_b32_e32 v48, v0
	v_mov_b32_e32 v49, v0
	v_mov_b32_e32 v50, v0
	v_mov_b32_e32 v51, v0
	v_mov_b32_e32 v52, v0
	v_mov_b32_e32 v53, v0
	v_mov_b32_e32 v54, v0
	v_mov_b32_e32 v55, v0
	v_mov_b32_e32 v8, v0
	v_mov_b32_e32 v9, v0
	v_mov_b32_e32 v10, v0
	v_mov_b32_e32 v11, v0
	v_mov_b32_e32 v12, v0
	v_mov_b32_e32 v13, v0
	v_mov_b32_e32 v14, v0
	v_mov_b32_e32 v15, v0
	v_mov_b32_e32 v24, v0
	v_mov_b32_e32 v25, v0
	v_mov_b32_e32 v26, v0
	v_mov_b32_e32 v27, v0
	v_mov_b32_e32 v28, v0
	v_mov_b32_e32 v29, v0
	v_mov_b32_e32 v30, v0
	v_mov_b32_e32 v31, v0
	v_mov_b32_e32 v40, v0
	v_mov_b32_e32 v41, v0
	v_mov_b32_e32 v42, v0
	v_mov_b32_e32 v43, v0
	v_mov_b32_e32 v44, v0
	v_mov_b32_e32 v45, v0
	v_mov_b32_e32 v46, v0
	v_mov_b32_e32 v47, v0
	v_mov_b32_e32 v56, v0
	v_mov_b32_e32 v57, v0
	v_mov_b32_e32 v58, v0
	v_mov_b32_e32 v59, v0
	v_mov_b32_e32 v60, v0
	v_mov_b32_e32 v61, v0
	v_mov_b32_e32 v62, v0
	v_mov_b32_e32 v63, v0
	v_mov_b32_e32 v64, v0
	v_mov_b32_e32 v65, v0
	v_mov_b32_e32 v66, v0
	v_mov_b32_e32 v67, v0
	v_mov_b32_e32 v68, v0
	v_mov_b32_e32 v69, v0
	v_mov_b32_e32 v70, v0
	v_mov_b32_e32 v71, v0
	v_mov_b32_e32 v80, v0
	v_mov_b32_e32 v81, v0
	v_mov_b32_e32 v82, v0
	v_mov_b32_e32 v83, v0
	v_mov_b32_e32 v84, v0
	v_mov_b32_e32 v85, v0
	v_mov_b32_e32 v86, v0
	v_mov_b32_e32 v87, v0
	v_mov_b32_e32 v96, v0
	v_mov_b32_e32 v97, v0
	v_mov_b32_e32 v98, v0
	v_mov_b32_e32 v99, v0
	v_mov_b32_e32 v100, v0
	v_mov_b32_e32 v101, v0
	v_mov_b32_e32 v102, v0
	v_mov_b32_e32 v103, v0
	v_mov_b32_e32 v112, v0
	v_mov_b32_e32 v113, v0
	v_mov_b32_e32 v114, v0
	v_mov_b32_e32 v115, v0
	v_mov_b32_e32 v116, v0
	v_mov_b32_e32 v117, v0
	v_mov_b32_e32 v118, v0
	v_mov_b32_e32 v119, v0
	v_mov_b32_e32 v72, v0
	v_mov_b32_e32 v73, v0
	v_mov_b32_e32 v74, v0
	v_mov_b32_e32 v75, v0
	v_mov_b32_e32 v76, v0
	v_mov_b32_e32 v77, v0
	v_mov_b32_e32 v78, v0
	v_mov_b32_e32 v79, v0
	v_mov_b32_e32 v88, v0
	v_mov_b32_e32 v89, v0
	v_mov_b32_e32 v90, v0
	v_mov_b32_e32 v91, v0
	v_mov_b32_e32 v92, v0
	v_mov_b32_e32 v93, v0
	v_mov_b32_e32 v94, v0
	v_mov_b32_e32 v95, v0
	v_mov_b32_e32 v104, v0
	v_mov_b32_e32 v105, v0
	v_mov_b32_e32 v106, v0
	v_mov_b32_e32 v107, v0
	v_mov_b32_e32 v108, v0
	v_mov_b32_e32 v109, v0
	v_mov_b32_e32 v110, v0
	v_mov_b32_e32 v111, v0
	v_mov_b32_e32 v120, v0
	v_mov_b32_e32 v121, v0
	v_mov_b32_e32 v122, v0
	v_mov_b32_e32 v123, v0
	v_mov_b32_e32 v124, v0
	v_mov_b32_e32 v125, v0
	v_mov_b32_e32 v126, v0
	v_mov_b32_e32 v127, v0
	v_readlane_b32 s26, v254, 6
	s_nop 3
	s_cmp_ge_u32 s26, 0x100
	s_cbranch_scc1 .Lsprio_p1
	s_setprio 1
.Lsprio_p1:
.LBB0_123:
	ds_read_b128 v[128:131], v190
	ds_read_b128 v[132:135], v190 offset:1024
	ds_read_b128 v[136:139], v190 offset:2048
	ds_read_b128 v[140:143], v190 offset:3072
	ds_read_b128 v[144:147], v191
	ds_read_b128 v[160:163], v191 offset:1024
	ds_read_b128 v[164:167], v191 offset:2048
	s_waitcnt lgkmcnt(0)
	ds_read_b128 v[168:171], v191 offset:3072
	s_add_u32 s4, s0, 0xfff80080
	s_addc_u32 s5, s1, -1
	s_cmp_eq_u32 s78, 28
	s_cselect_b32 s73, s69, s5
	s_cselect_b32 s72, s68, s4
	s_cselect_b32 s5, s71, s67
	s_cselect_b32 s4, s70, s65
	s_add_i32 s94, s33, 0xc000
	v_lshl_add_u64 v[184:185], s[0:1], 0, v[156:157]
	s_mov_b32 m0, s94
	s_add_i32 s95, s33, 0xe000
	ds_read_b128 v[172:175], v192
	ds_read_b128 v[176:179], v192 offset:1024
	ds_read_b128 v[180:183], v192 offset:2048
	ds_read_b128 v[194:197], v192 offset:3072
	ds_read_b128 v[198:201], v192 offset:4096
	ds_read_b128 v[202:205], v192 offset:5120
	ds_read_b128 v[206:209], v192 offset:6144
	ds_read_b128 v[210:213], v192 offset:7168
	global_load_lds_dwordx4 v[184:185], off
	v_lshl_add_u64 v[184:185], s[0:1], 0, v[158:159]
	s_mov_b32 m0, s95
	s_nop 0
	global_load_lds_dwordx4 v[184:185], off
	s_waitcnt vmcnt(8)
	s_waitcnt lgkmcnt(0)
	s_barrier
	s_waitcnt lgkmcnt(0)
	v_mfma_f32_16x16x32_bf16 v[124:127], v[128:131], v[172:175], v[124:127]
	v_mfma_f32_16x16x32_bf16 v[120:123], v[136:139], v[172:175], v[120:123]
	v_mfma_f32_16x16x32_bf16 v[108:111], v[128:131], v[180:183], v[108:111]
	v_mfma_f32_16x16x32_bf16 v[104:107], v[136:139], v[180:183], v[104:107]
	v_mfma_f32_16x16x32_bf16 v[92:95], v[128:131], v[198:201], v[92:95]
	v_mfma_f32_16x16x32_bf16 v[88:91], v[136:139], v[198:201], v[88:91]
	v_mfma_f32_16x16x32_bf16 v[76:79], v[128:131], v[206:209], v[76:79]
	v_mfma_f32_16x16x32_bf16 v[72:75], v[136:139], v[206:209], v[72:75]
	v_mfma_f32_16x16x32_bf16 v[124:127], v[132:135], v[176:179], v[124:127]
	v_mfma_f32_16x16x32_bf16 v[120:123], v[140:143], v[176:179], v[120:123]
	v_mfma_f32_16x16x32_bf16 v[108:111], v[132:135], v[194:197], v[108:111]
	v_mfma_f32_16x16x32_bf16 v[104:107], v[140:143], v[194:197], v[104:107]
	v_mfma_f32_16x16x32_bf16 v[92:95], v[132:135], v[202:205], v[92:95]
	v_mfma_f32_16x16x32_bf16 v[88:91], v[140:143], v[202:205], v[88:91]
	v_mfma_f32_16x16x32_bf16 v[76:79], v[132:135], v[210:213], v[76:79]
	v_mfma_f32_16x16x32_bf16 v[72:75], v[140:143], v[210:213], v[72:75]
	v_mfma_f32_16x16x32_bf16 v[116:119], v[144:147], v[172:175], v[116:119]
	v_mfma_f32_16x16x32_bf16 v[112:115], v[164:167], v[172:175], v[112:115]
	v_mfma_f32_16x16x32_bf16 v[100:103], v[144:147], v[180:183], v[100:103]
	v_mfma_f32_16x16x32_bf16 v[96:99], v[164:167], v[180:183], v[96:99]
	v_mfma_f32_16x16x32_bf16 v[84:87], v[144:147], v[198:201], v[84:87]
	v_mfma_f32_16x16x32_bf16 v[80:83], v[164:167], v[198:201], v[80:83]
	v_mfma_f32_16x16x32_bf16 v[68:71], v[144:147], v[206:209], v[68:71]
	v_mfma_f32_16x16x32_bf16 v[64:67], v[164:167], v[206:209], v[64:67]
	v_mfma_f32_16x16x32_bf16 v[116:119], v[160:163], v[176:179], v[116:119]
	v_mfma_f32_16x16x32_bf16 v[112:115], v[168:171], v[176:179], v[112:115]
	v_mfma_f32_16x16x32_bf16 v[100:103], v[160:163], v[194:197], v[100:103]
	v_mfma_f32_16x16x32_bf16 v[96:99], v[168:171], v[194:197], v[96:99]
	v_mfma_f32_16x16x32_bf16 v[84:87], v[160:163], v[202:205], v[84:87]
	v_mfma_f32_16x16x32_bf16 v[80:83], v[168:171], v[202:205], v[80:83]
	v_mfma_f32_16x16x32_bf16 v[68:71], v[160:163], v[210:213], v[68:71]
	v_mfma_f32_16x16x32_bf16 v[64:67], v[168:171], v[210:213], v[64:67]
	s_barrier
	s_add_i32 s96, s31, s40
	s_add_i32 s97, s96, 0x2000
	v_lshl_add_u64 v[184:185], s[4:5], 0, v[150:151]
	s_mov_b32 m0, s96
	s_add_u32 s26, s4, 0x80000
	ds_read_b128 v[172:175], v192 offset:16384
	ds_read_b128 v[176:179], v192 offset:17408
	ds_read_b128 v[180:183], v192 offset:18432
	ds_read_b128 v[194:197], v192 offset:19456
	ds_read_b128 v[198:201], v192 offset:20480
	ds_read_b128 v[202:205], v192 offset:21504
	ds_read_b128 v[206:209], v192 offset:22528
	ds_read_b128 v[210:213], v192 offset:23552
	global_load_lds_dwordx4 v[184:185], off
	v_lshl_add_u64 v[214:215], s[4:5], 0, v[154:155]
	s_mov_b32 m0, s97
	s_addc_u32 s27, s5, 0
	s_add_i32 s91, s30, s40
	global_load_lds_dwordx4 v[214:215], off
	v_lshl_add_u64 v[216:217], s[26:27], 0, v[150:151]
	s_mov_b32 m0, s91
	v_lshl_add_u64 v[218:219], s[72:73], 0, v[152:153]
	global_load_lds_dwordx4 v[216:217], off
	v_lshl_add_u64 v[216:217], s[26:27], 0, v[154:155]
	s_add_i32 s26, s91, 0x2000
	s_mov_b32 m0, s26
	s_nop 0
	global_load_lds_dwordx4 v[216:217], off
	v_lshl_add_u64 v[216:217], s[72:73], 0, v[148:149]
	s_mov_b32 m0, s33
	s_nop 0
	global_load_lds_dwordx4 v[216:217], off
	s_mov_b32 m0, s88
	s_nop 0
	global_load_lds_dwordx4 v[218:219], off
	s_waitcnt vmcnt(8)
	s_waitcnt lgkmcnt(0)
	s_barrier
	s_waitcnt lgkmcnt(0)
	v_mfma_f32_16x16x32_bf16 v[60:63], v[128:131], v[172:175], v[60:63]
	v_mfma_f32_16x16x32_bf16 v[56:59], v[136:139], v[172:175], v[56:59]
	v_mfma_f32_16x16x32_bf16 v[44:47], v[128:131], v[180:183], v[44:47]
	v_mfma_f32_16x16x32_bf16 v[40:43], v[136:139], v[180:183], v[40:43]
	v_mfma_f32_16x16x32_bf16 v[28:31], v[128:131], v[198:201], v[28:31]
	v_mfma_f32_16x16x32_bf16 v[24:27], v[136:139], v[198:201], v[24:27]
	v_mfma_f32_16x16x32_bf16 v[12:15], v[128:131], v[206:209], v[12:15]
	v_mfma_f32_16x16x32_bf16 v[8:11], v[136:139], v[206:209], v[8:11]
	v_mfma_f32_16x16x32_bf16 v[60:63], v[132:135], v[176:179], v[60:63]
	v_mfma_f32_16x16x32_bf16 v[56:59], v[140:143], v[176:179], v[56:59]
	v_mfma_f32_16x16x32_bf16 v[44:47], v[132:135], v[194:197], v[44:47]
	v_mfma_f32_16x16x32_bf16 v[40:43], v[140:143], v[194:197], v[40:43]
	v_mfma_f32_16x16x32_bf16 v[28:31], v[132:135], v[202:205], v[28:31]
	v_mfma_f32_16x16x32_bf16 v[24:27], v[140:143], v[202:205], v[24:27]
	v_mfma_f32_16x16x32_bf16 v[12:15], v[132:135], v[210:213], v[12:15]
	v_mfma_f32_16x16x32_bf16 v[8:11], v[140:143], v[210:213], v[8:11]
	v_mfma_f32_16x16x32_bf16 v[52:55], v[144:147], v[172:175], v[52:55]
	v_mfma_f32_16x16x32_bf16 v[48:51], v[164:167], v[172:175], v[48:51]
	v_mfma_f32_16x16x32_bf16 v[36:39], v[144:147], v[180:183], v[36:39]
	v_mfma_f32_16x16x32_bf16 v[32:35], v[164:167], v[180:183], v[32:35]
	v_mfma_f32_16x16x32_bf16 v[20:23], v[144:147], v[198:201], v[20:23]
	v_mfma_f32_16x16x32_bf16 v[16:19], v[164:167], v[198:201], v[16:19]
	v_mfma_f32_16x16x32_bf16 v[4:7], v[144:147], v[206:209], v[4:7]
	v_mfma_f32_16x16x32_bf16 v[0:3], v[164:167], v[206:209], v[0:3]
	v_mfma_f32_16x16x32_bf16 v[52:55], v[160:163], v[176:179], v[52:55]
	v_mfma_f32_16x16x32_bf16 v[48:51], v[168:171], v[176:179], v[48:51]
	v_mfma_f32_16x16x32_bf16 v[36:39], v[160:163], v[194:197], v[36:39]
	v_mfma_f32_16x16x32_bf16 v[32:35], v[168:171], v[194:197], v[32:35]
	v_mfma_f32_16x16x32_bf16 v[20:23], v[160:163], v[202:205], v[20:23]
	v_mfma_f32_16x16x32_bf16 v[16:19], v[168:171], v[202:205], v[16:19]
	v_mfma_f32_16x16x32_bf16 v[4:7], v[160:163], v[210:213], v[4:7]
	v_mfma_f32_16x16x32_bf16 v[0:3], v[168:171], v[210:213], v[0:3]
	s_barrier
	s_add_i32 s29, 0, 0x18000
	s_add_i32 s41, 0, 0x1c000
	v_add_u32_e32 v140, s29, v189
	v_add_u32_e32 v168, s41, v189
	ds_read_b128 v[128:131], v140
	ds_read_b128 v[132:135], v140 offset:1024
	ds_read_b128 v[136:139], v140 offset:2048
	ds_read_b128 v[140:143], v140 offset:3072
	ds_read_b128 v[144:147], v168
	ds_read_b128 v[160:163], v168 offset:1024
	ds_read_b128 v[164:167], v168 offset:2048
	ds_read_b128 v[168:171], v168 offset:3072
	s_add_u32 s34, s72, 0x80000
	s_addc_u32 s35, s73, 0
	s_mov_b32 m0, s89
	v_lshl_add_u64 v[220:221], s[34:35], 0, v[148:149]
	ds_read_b128 v[172:175], v192 offset:32768
	ds_read_b128 v[176:179], v192 offset:33792
	ds_read_b128 v[180:183], v192 offset:34816
	ds_read_b128 v[194:197], v192 offset:35840
	ds_read_b128 v[198:201], v192 offset:36864
	ds_read_b128 v[202:205], v192 offset:37888
	ds_read_b128 v[206:209], v192 offset:38912
	ds_read_b128 v[210:213], v192 offset:39936
	global_load_lds_dwordx4 v[220:221], off
	v_lshl_add_u64 v[220:221], s[34:35], 0, v[152:153]
	s_mov_b32 m0, s90
	s_nop 0
	global_load_lds_dwordx4 v[220:221], off
	s_waitcnt vmcnt(8)
	s_waitcnt lgkmcnt(0)
	s_barrier
	s_waitcnt lgkmcnt(0)
	v_mfma_f32_16x16x32_bf16 v[124:127], v[128:131], v[172:175], v[124:127]
	v_mfma_f32_16x16x32_bf16 v[120:123], v[136:139], v[172:175], v[120:123]
	v_mfma_f32_16x16x32_bf16 v[108:111], v[128:131], v[180:183], v[108:111]
	v_mfma_f32_16x16x32_bf16 v[104:107], v[136:139], v[180:183], v[104:107]
	v_mfma_f32_16x16x32_bf16 v[92:95], v[128:131], v[198:201], v[92:95]
	v_mfma_f32_16x16x32_bf16 v[88:91], v[136:139], v[198:201], v[88:91]
	v_mfma_f32_16x16x32_bf16 v[76:79], v[128:131], v[206:209], v[76:79]
	v_mfma_f32_16x16x32_bf16 v[72:75], v[136:139], v[206:209], v[72:75]
	v_mfma_f32_16x16x32_bf16 v[124:127], v[132:135], v[176:179], v[124:127]
	v_mfma_f32_16x16x32_bf16 v[120:123], v[140:143], v[176:179], v[120:123]
	v_mfma_f32_16x16x32_bf16 v[108:111], v[132:135], v[194:197], v[108:111]
	v_mfma_f32_16x16x32_bf16 v[104:107], v[140:143], v[194:197], v[104:107]
	v_mfma_f32_16x16x32_bf16 v[92:95], v[132:135], v[202:205], v[92:95]
	v_mfma_f32_16x16x32_bf16 v[88:91], v[140:143], v[202:205], v[88:91]
	v_mfma_f32_16x16x32_bf16 v[76:79], v[132:135], v[210:213], v[76:79]
	v_mfma_f32_16x16x32_bf16 v[72:75], v[140:143], v[210:213], v[72:75]
	v_mfma_f32_16x16x32_bf16 v[116:119], v[144:147], v[172:175], v[116:119]
	v_mfma_f32_16x16x32_bf16 v[112:115], v[164:167], v[172:175], v[112:115]
	v_mfma_f32_16x16x32_bf16 v[100:103], v[144:147], v[180:183], v[100:103]
	v_mfma_f32_16x16x32_bf16 v[96:99], v[164:167], v[180:183], v[96:99]
	v_mfma_f32_16x16x32_bf16 v[84:87], v[144:147], v[198:201], v[84:87]
	v_mfma_f32_16x16x32_bf16 v[80:83], v[164:167], v[198:201], v[80:83]
	v_mfma_f32_16x16x32_bf16 v[68:71], v[144:147], v[206:209], v[68:71]
	v_mfma_f32_16x16x32_bf16 v[64:67], v[164:167], v[206:209], v[64:67]
	v_mfma_f32_16x16x32_bf16 v[116:119], v[160:163], v[176:179], v[116:119]
	v_mfma_f32_16x16x32_bf16 v[112:115], v[168:171], v[176:179], v[112:115]
	v_mfma_f32_16x16x32_bf16 v[100:103], v[160:163], v[194:197], v[100:103]
	v_mfma_f32_16x16x32_bf16 v[96:99], v[168:171], v[194:197], v[96:99]
	v_mfma_f32_16x16x32_bf16 v[84:87], v[160:163], v[202:205], v[84:87]
	v_mfma_f32_16x16x32_bf16 v[80:83], v[168:171], v[202:205], v[80:83]
	v_mfma_f32_16x16x32_bf16 v[68:71], v[160:163], v[210:213], v[68:71]
	v_mfma_f32_16x16x32_bf16 v[64:67], v[168:171], v[210:213], v[64:67]
	s_barrier
	s_add_i32 s27, s29, s40
	s_add_i32 s34, s27, 0x2000
	v_lshl_add_u64 v[184:185], v[184:185], 0, s[48:49]
	s_mov_b32 m0, s27
	s_add_u32 s4, s4, 0x80080
	ds_read_b128 v[172:175], v192 offset:49152
	ds_read_b128 v[176:179], v192 offset:50176
	ds_read_b128 v[180:183], v192 offset:51200
	ds_read_b128 v[194:197], v192 offset:52224
	ds_read_b128 v[198:201], v192 offset:53248
	ds_read_b128 v[202:205], v192 offset:54272
	ds_read_b128 v[206:209], v192 offset:55296
	ds_read_b128 v[210:213], v192 offset:56320
	global_load_lds_dwordx4 v[184:185], off
	v_lshl_add_u64 v[184:185], v[214:215], 0, s[48:49]
	s_mov_b32 m0, s34
	s_addc_u32 s5, s5, 0
	s_add_i32 s35, s41, s40
	global_load_lds_dwordx4 v[184:185], off
	v_lshl_add_u64 v[184:185], s[4:5], 0, v[150:151]
	s_mov_b32 m0, s35
	s_add_i32 s28, s35, 0x2000
	global_load_lds_dwordx4 v[184:185], off
	v_lshl_add_u64 v[184:185], s[4:5], 0, v[154:155]
	s_mov_b32 m0, s28
	s_nop 0
	global_load_lds_dwordx4 v[184:185], off
	v_lshl_add_u64 v[184:185], v[216:217], 0, s[48:49]
	s_mov_b32 m0, s92
	s_nop 0
	global_load_lds_dwordx4 v[184:185], off
	v_lshl_add_u64 v[184:185], v[218:219], 0, s[48:49]
	s_mov_b32 m0, s93
	s_nop 0
	global_load_lds_dwordx4 v[184:185], off
	s_waitcnt vmcnt(8)
	s_waitcnt lgkmcnt(0)
	s_barrier
	s_waitcnt lgkmcnt(0)
	v_mfma_f32_16x16x32_bf16 v[60:63], v[128:131], v[172:175], v[60:63]
	v_mfma_f32_16x16x32_bf16 v[56:59], v[136:139], v[172:175], v[56:59]
	v_mfma_f32_16x16x32_bf16 v[44:47], v[128:131], v[180:183], v[44:47]
	v_mfma_f32_16x16x32_bf16 v[40:43], v[136:139], v[180:183], v[40:43]
	v_mfma_f32_16x16x32_bf16 v[28:31], v[128:131], v[198:201], v[28:31]
	v_mfma_f32_16x16x32_bf16 v[24:27], v[136:139], v[198:201], v[24:27]
	v_mfma_f32_16x16x32_bf16 v[12:15], v[128:131], v[206:209], v[12:15]
	v_mfma_f32_16x16x32_bf16 v[8:11], v[136:139], v[206:209], v[8:11]
	v_mfma_f32_16x16x32_bf16 v[60:63], v[132:135], v[176:179], v[60:63]
	v_mfma_f32_16x16x32_bf16 v[56:59], v[140:143], v[176:179], v[56:59]
	v_mfma_f32_16x16x32_bf16 v[44:47], v[132:135], v[194:197], v[44:47]
	v_mfma_f32_16x16x32_bf16 v[40:43], v[140:143], v[194:197], v[40:43]
	v_mfma_f32_16x16x32_bf16 v[28:31], v[132:135], v[202:205], v[28:31]
	v_mfma_f32_16x16x32_bf16 v[24:27], v[140:143], v[202:205], v[24:27]
	v_mfma_f32_16x16x32_bf16 v[12:15], v[132:135], v[210:213], v[12:15]
	v_mfma_f32_16x16x32_bf16 v[8:11], v[140:143], v[210:213], v[8:11]
	v_mfma_f32_16x16x32_bf16 v[52:55], v[144:147], v[172:175], v[52:55]
	v_mfma_f32_16x16x32_bf16 v[48:51], v[164:167], v[172:175], v[48:51]
	v_mfma_f32_16x16x32_bf16 v[36:39], v[144:147], v[180:183], v[36:39]
	v_mfma_f32_16x16x32_bf16 v[32:35], v[164:167], v[180:183], v[32:35]
	v_mfma_f32_16x16x32_bf16 v[20:23], v[144:147], v[198:201], v[20:23]
	v_mfma_f32_16x16x32_bf16 v[16:19], v[164:167], v[198:201], v[16:19]
	v_mfma_f32_16x16x32_bf16 v[4:7], v[144:147], v[206:209], v[4:7]
	v_mfma_f32_16x16x32_bf16 v[0:3], v[164:167], v[206:209], v[0:3]
	v_mfma_f32_16x16x32_bf16 v[52:55], v[160:163], v[176:179], v[52:55]
	v_mfma_f32_16x16x32_bf16 v[48:51], v[168:171], v[176:179], v[48:51]
	v_mfma_f32_16x16x32_bf16 v[36:39], v[160:163], v[194:197], v[36:39]
	v_mfma_f32_16x16x32_bf16 v[32:35], v[168:171], v[194:197], v[32:35]
	v_mfma_f32_16x16x32_bf16 v[20:23], v[160:163], v[202:205], v[20:23]
	v_mfma_f32_16x16x32_bf16 v[16:19], v[168:171], v[202:205], v[16:19]
	v_mfma_f32_16x16x32_bf16 v[4:7], v[160:163], v[210:213], v[4:7]
	v_mfma_f32_16x16x32_bf16 v[0:3], v[168:171], v[210:213], v[0:3]
	s_barrier
	s_add_i32 s78, s78, 2
	s_add_u32 s0, s0, 0x100
	s_addc_u32 s1, s1, 0
	s_add_u32 s65, s65, 0x100
	s_addc_u32 s67, s67, 0
	s_cmp_gt_u32 s78, 29
	s_cbranch_scc0 .LBB0_123
	s_setprio 0
	s_and_b64 vcc, exec, s[42:43]
	s_cbranch_vccz .LBB0_126
	s_barrier

.LBB0_412:
	s_add_u32 s50, s50, 0x80080
	s_addc_u32 s51, s51, 0
	s_add_u32 s23, s52, 0x100
	v_mov_b32_e32 v0, 0
	s_addc_u32 s25, s53, 0
	s_mov_b32 s45, -2
	s_waitcnt lgkmcnt(0)
	v_mov_b32_e32 v1, v0
	v_mov_b32_e32 v2, v0
	v_mov_b32_e32 v3, v0
	v_mov_b32_e32 v4, v0
	v_mov_b32_e32 v5, v0
	v_mov_b32_e32 v6, v0
	v_mov_b32_e32 v7, v0
	v_mov_b32_e32 v16, v0
	v_mov_b32_e32 v17, v0
	v_mov_b32_e32 v18, v0
	v_mov_b32_e32 v19, v0
	v_mov_b32_e32 v20, v0
	v_mov_b32_e32 v21, v0
	v_mov_b32_e32 v22, v0
	v_mov_b32_e32 v23, v0
	v_mov_b32_e32 v32, v0
	v_mov_b32_e32 v33, v0
	v_mov_b32_e32 v34, v0
	v_mov_b32_e32 v35, v0
	v_mov_b32_e32 v36, v0
	v_mov_b32_e32 v37, v0
	v_mov_b32_e32 v38, v0
	v_mov_b32_e32 v39, v0
	v_mov_b32_e32 v48, v0
	v_mov_b32_e32 v49, v0
	v_mov_b32_e32 v50, v0
	v_mov_b32_e32 v51, v0
	v_mov_b32_e32 v52, v0
	v_mov_b32_e32 v53, v0
	v_mov_b32_e32 v54, v0
	v_mov_b32_e32 v55, v0
	v_mov_b32_e32 v8, v0
	v_mov_b32_e32 v9, v0
	v_mov_b32_e32 v10, v0
	v_mov_b32_e32 v11, v0
	v_mov_b32_e32 v12, v0
	v_mov_b32_e32 v13, v0
	v_mov_b32_e32 v14, v0
	v_mov_b32_e32 v15, v0
	v_mov_b32_e32 v24, v0
	v_mov_b32_e32 v25, v0
	v_mov_b32_e32 v26, v0
	v_mov_b32_e32 v27, v0
	v_mov_b32_e32 v28, v0
	v_mov_b32_e32 v29, v0
	v_mov_b32_e32 v30, v0
	v_mov_b32_e32 v31, v0
	v_mov_b32_e32 v40, v0
	v_mov_b32_e32 v41, v0
	v_mov_b32_e32 v42, v0
	v_mov_b32_e32 v43, v0
	v_mov_b32_e32 v44, v0
	v_mov_b32_e32 v45, v0
	v_mov_b32_e32 v46, v0
	v_mov_b32_e32 v47, v0
	v_mov_b32_e32 v56, v0
	v_mov_b32_e32 v57, v0
	v_mov_b32_e32 v58, v0
	v_mov_b32_e32 v59, v0
	v_mov_b32_e32 v60, v0
	v_mov_b32_e32 v61, v0
	v_mov_b32_e32 v62, v0
	v_mov_b32_e32 v63, v0
	v_mov_b32_e32 v64, v0
	v_mov_b32_e32 v65, v0
	v_mov_b32_e32 v66, v0
	v_mov_b32_e32 v67, v0
	v_mov_b32_e32 v68, v0
	v_mov_b32_e32 v69, v0
	v_mov_b32_e32 v70, v0
	v_mov_b32_e32 v71, v0
	v_mov_b32_e32 v80, v0
	v_mov_b32_e32 v81, v0
	v_mov_b32_e32 v82, v0
	v_mov_b32_e32 v83, v0
	v_mov_b32_e32 v84, v0
	v_mov_b32_e32 v85, v0
	v_mov_b32_e32 v86, v0
	v_mov_b32_e32 v87, v0
	v_mov_b32_e32 v96, v0
	v_mov_b32_e32 v97, v0
	v_mov_b32_e32 v98, v0
	v_mov_b32_e32 v99, v0
	v_mov_b32_e32 v100, v0
	v_mov_b32_e32 v101, v0
	v_mov_b32_e32 v102, v0
	v_mov_b32_e32 v103, v0
	v_mov_b32_e32 v112, v0
	v_mov_b32_e32 v113, v0
	v_mov_b32_e32 v114, v0
	v_mov_b32_e32 v115, v0
	v_mov_b32_e32 v116, v0
	v_mov_b32_e32 v117, v0
	v_mov_b32_e32 v118, v0
	v_mov_b32_e32 v119, v0
	v_mov_b32_e32 v72, v0
	v_mov_b32_e32 v73, v0
	v_mov_b32_e32 v74, v0
	v_mov_b32_e32 v75, v0
	v_mov_b32_e32 v76, v0
	v_mov_b32_e32 v77, v0
	v_mov_b32_e32 v78, v0
	v_mov_b32_e32 v79, v0
	v_mov_b32_e32 v88, v0
	v_mov_b32_e32 v89, v0
	v_mov_b32_e32 v90, v0
	v_mov_b32_e32 v91, v0
	v_mov_b32_e32 v92, v0
	v_mov_b32_e32 v93, v0
	v_mov_b32_e32 v94, v0
	v_mov_b32_e32 v95, v0
	v_mov_b32_e32 v104, v0
	v_mov_b32_e32 v105, v0
	v_mov_b32_e32 v106, v0
	v_mov_b32_e32 v107, v0
	v_mov_b32_e32 v108, v0
	v_mov_b32_e32 v109, v0
	v_mov_b32_e32 v110, v0
	v_mov_b32_e32 v111, v0
	v_mov_b32_e32 v120, v0
	v_mov_b32_e32 v121, v0
	v_mov_b32_e32 v122, v0
	v_mov_b32_e32 v123, v0
	v_mov_b32_e32 v124, v0
	v_mov_b32_e32 v125, v0
	v_mov_b32_e32 v126, v0
	v_mov_b32_e32 v127, v0
	v_readlane_b32 s52, v254, 6
	s_nop 3
	s_cmp_ge_u32 s52, 0x100
	s_cbranch_scc1 .Lsprio_p4
	s_setprio 1
.Lsprio_p4:
.LBB0_413:
	ds_read_b128 v[144:147], v155
	ds_read_b128 v[148:151], v155 offset:1024
	ds_read_b128 v[158:161], v155 offset:2048
	ds_read_b128 v[162:165], v155 offset:3072
	ds_read_b128 v[166:169], v156
	ds_read_b128 v[170:173], v156 offset:1024
	ds_read_b128 v[174:177], v156 offset:2048
	ds_read_b128 v[178:181], v156 offset:3072
	s_add_u32 s21, s50, 0xfff80080
	s_addc_u32 s52, s51, -1
	s_cmp_eq_u32 s45, 28
	s_cselect_b32 s55, s9, s52
	s_cselect_b32 s54, s8, s21
	s_cselect_b32 s53, s43, s25
	s_cselect_b32 s52, s42, s23
	s_add_u32 s58, s52, 0x80000
	s_addc_u32 s59, s53, 0
	s_mov_b32 m0, s94
	ds_read_b128 v[182:185], v157
	ds_read_b128 v[188:191], v157 offset:1024
	ds_read_b128 v[192:195], v157 offset:2048
	ds_read_b128 v[196:199], v157 offset:3072
	ds_read_b128 v[200:203], v157 offset:4096
	ds_read_b128 v[204:207], v157 offset:5120
	ds_read_b128 v[208:211], v157 offset:6144
	ds_read_b128 v[212:215], v157 offset:7168
	global_load_lds_dwordx4 v136, s[50:51]
	s_mov_b32 m0, s95
	s_nop 0
	global_load_lds_dwordx4 v138, s[50:51]
	s_waitcnt vmcnt(8)
	s_waitcnt lgkmcnt(0)
	s_barrier
	s_waitcnt lgkmcnt(0)
	v_mfma_f32_16x16x32_bf16 v[124:127], v[144:147], v[182:185], v[124:127]
	v_mfma_f32_16x16x32_bf16 v[120:123], v[158:161], v[182:185], v[120:123]
	v_mfma_f32_16x16x32_bf16 v[108:111], v[144:147], v[192:195], v[108:111]
	v_mfma_f32_16x16x32_bf16 v[104:107], v[158:161], v[192:195], v[104:107]
	v_mfma_f32_16x16x32_bf16 v[92:95], v[144:147], v[200:203], v[92:95]
	v_mfma_f32_16x16x32_bf16 v[88:91], v[158:161], v[200:203], v[88:91]
	v_mfma_f32_16x16x32_bf16 v[76:79], v[144:147], v[208:211], v[76:79]
	v_mfma_f32_16x16x32_bf16 v[72:75], v[158:161], v[208:211], v[72:75]
	v_mfma_f32_16x16x32_bf16 v[124:127], v[148:151], v[188:191], v[124:127]
	v_mfma_f32_16x16x32_bf16 v[120:123], v[162:165], v[188:191], v[120:123]
	v_mfma_f32_16x16x32_bf16 v[108:111], v[148:151], v[196:199], v[108:111]
	v_mfma_f32_16x16x32_bf16 v[104:107], v[162:165], v[196:199], v[104:107]
	v_mfma_f32_16x16x32_bf16 v[92:95], v[148:151], v[204:207], v[92:95]
	v_mfma_f32_16x16x32_bf16 v[88:91], v[162:165], v[204:207], v[88:91]
	v_mfma_f32_16x16x32_bf16 v[76:79], v[148:151], v[212:215], v[76:79]
	v_mfma_f32_16x16x32_bf16 v[72:75], v[162:165], v[212:215], v[72:75]
	v_mfma_f32_16x16x32_bf16 v[116:119], v[166:169], v[182:185], v[116:119]
	v_mfma_f32_16x16x32_bf16 v[112:115], v[174:177], v[182:185], v[112:115]
	v_mfma_f32_16x16x32_bf16 v[100:103], v[166:169], v[192:195], v[100:103]
	v_mfma_f32_16x16x32_bf16 v[96:99], v[174:177], v[192:195], v[96:99]
	v_mfma_f32_16x16x32_bf16 v[84:87], v[166:169], v[200:203], v[84:87]
	v_mfma_f32_16x16x32_bf16 v[80:83], v[174:177], v[200:203], v[80:83]
	v_mfma_f32_16x16x32_bf16 v[68:71], v[166:169], v[208:211], v[68:71]
	v_mfma_f32_16x16x32_bf16 v[64:67], v[174:177], v[208:211], v[64:67]
	v_mfma_f32_16x16x32_bf16 v[116:119], v[170:173], v[188:191], v[116:119]
	v_mfma_f32_16x16x32_bf16 v[112:115], v[178:181], v[188:191], v[112:115]
	v_mfma_f32_16x16x32_bf16 v[100:103], v[170:173], v[196:199], v[100:103]
	v_mfma_f32_16x16x32_bf16 v[96:99], v[178:181], v[196:199], v[96:99]
	v_mfma_f32_16x16x32_bf16 v[84:87], v[170:173], v[204:207], v[84:87]
	v_mfma_f32_16x16x32_bf16 v[80:83], v[178:181], v[204:207], v[80:83]
	v_mfma_f32_16x16x32_bf16 v[68:71], v[170:173], v[212:215], v[68:71]
	v_mfma_f32_16x16x32_bf16 v[64:67], v[178:181], v[212:215], v[64:67]
	s_barrier
	s_mov_b32 m0, s96
	s_add_u32 s98, s54, 0x80000
	s_addc_u32 s99, s55, 0
	ds_read_b128 v[182:185], v157 offset:16384
	ds_read_b128 v[188:191], v157 offset:17408
	ds_read_b128 v[192:195], v157 offset:18432
	ds_read_b128 v[196:199], v157 offset:19456
	ds_read_b128 v[200:203], v157 offset:20480
	ds_read_b128 v[204:207], v157 offset:21504
	ds_read_b128 v[208:211], v157 offset:22528
	ds_read_b128 v[212:215], v157 offset:23552
	global_load_lds_dwordx4 v130, s[52:53]
	s_mov_b32 m0, s97
	s_nop 0
	global_load_lds_dwordx4 v134, s[52:53]
	s_mov_b32 m0, s91
	s_nop 0
	global_load_lds_dwordx4 v130, s[58:59]
	s_mov_b32 m0, s26
	s_nop 0
	global_load_lds_dwordx4 v134, s[58:59]
	s_mov_b32 m0, s33
	s_nop 0
	global_load_lds_dwordx4 v128, s[54:55]
	s_mov_b32 m0, s88
	s_nop 0
	global_load_lds_dwordx4 v132, s[54:55]
	s_waitcnt vmcnt(8)
	s_waitcnt lgkmcnt(0)
	s_barrier
	s_waitcnt lgkmcnt(0)
	v_mfma_f32_16x16x32_bf16 v[60:63], v[144:147], v[182:185], v[60:63]
	v_mfma_f32_16x16x32_bf16 v[56:59], v[158:161], v[182:185], v[56:59]
	v_mfma_f32_16x16x32_bf16 v[44:47], v[144:147], v[192:195], v[44:47]
	v_mfma_f32_16x16x32_bf16 v[40:43], v[158:161], v[192:195], v[40:43]
	v_mfma_f32_16x16x32_bf16 v[28:31], v[144:147], v[200:203], v[28:31]
	v_mfma_f32_16x16x32_bf16 v[24:27], v[158:161], v[200:203], v[24:27]
	v_mfma_f32_16x16x32_bf16 v[12:15], v[144:147], v[208:211], v[12:15]
	v_mfma_f32_16x16x32_bf16 v[8:11], v[158:161], v[208:211], v[8:11]
	v_mfma_f32_16x16x32_bf16 v[60:63], v[148:151], v[188:191], v[60:63]
	v_mfma_f32_16x16x32_bf16 v[56:59], v[162:165], v[188:191], v[56:59]
	v_mfma_f32_16x16x32_bf16 v[44:47], v[148:151], v[196:199], v[44:47]
	v_mfma_f32_16x16x32_bf16 v[40:43], v[162:165], v[196:199], v[40:43]
	v_mfma_f32_16x16x32_bf16 v[28:31], v[148:151], v[204:207], v[28:31]
	v_mfma_f32_16x16x32_bf16 v[24:27], v[162:165], v[204:207], v[24:27]
	v_mfma_f32_16x16x32_bf16 v[12:15], v[148:151], v[212:215], v[12:15]
	v_mfma_f32_16x16x32_bf16 v[8:11], v[162:165], v[212:215], v[8:11]
	v_mfma_f32_16x16x32_bf16 v[52:55], v[166:169], v[182:185], v[52:55]
	v_mfma_f32_16x16x32_bf16 v[48:51], v[174:177], v[182:185], v[48:51]
	v_mfma_f32_16x16x32_bf16 v[36:39], v[166:169], v[192:195], v[36:39]
	v_mfma_f32_16x16x32_bf16 v[32:35], v[174:177], v[192:195], v[32:35]
	v_mfma_f32_16x16x32_bf16 v[20:23], v[166:169], v[200:203], v[20:23]
	v_mfma_f32_16x16x32_bf16 v[16:19], v[174:177], v[200:203], v[16:19]
	v_mfma_f32_16x16x32_bf16 v[4:7], v[166:169], v[208:211], v[4:7]
	v_mfma_f32_16x16x32_bf16 v[0:3], v[174:177], v[208:211], v[0:3]
	v_mfma_f32_16x16x32_bf16 v[52:55], v[170:173], v[188:191], v[52:55]
	v_mfma_f32_16x16x32_bf16 v[48:51], v[178:181], v[188:191], v[48:51]
	v_mfma_f32_16x16x32_bf16 v[36:39], v[170:173], v[196:199], v[36:39]
	v_mfma_f32_16x16x32_bf16 v[32:35], v[178:181], v[196:199], v[32:35]
	v_mfma_f32_16x16x32_bf16 v[20:23], v[170:173], v[204:207], v[20:23]
	v_mfma_f32_16x16x32_bf16 v[16:19], v[178:181], v[204:207], v[16:19]
	v_mfma_f32_16x16x32_bf16 v[4:7], v[170:173], v[212:215], v[4:7]
	v_mfma_f32_16x16x32_bf16 v[0:3], v[178:181], v[212:215], v[0:3]
	s_barrier
	v_add_u32_e32 v162, s29, v153
	v_add_u32_e32 v178, s41, v153
	ds_read_b128 v[144:147], v162
	ds_read_b128 v[148:151], v162 offset:1024
	ds_read_b128 v[158:161], v162 offset:2048
	ds_read_b128 v[162:165], v162 offset:3072
	ds_read_b128 v[166:169], v178
	ds_read_b128 v[170:173], v178 offset:1024
	ds_read_b128 v[174:177], v178 offset:2048
	ds_read_b128 v[178:181], v178 offset:3072
	s_mov_b32 m0, s89
	s_add_u32 s100, s52, 0x80
	s_addc_u32 s101, s53, 0
	ds_read_b128 v[182:185], v157 offset:32768
	ds_read_b128 v[188:191], v157 offset:33792
	ds_read_b128 v[192:195], v157 offset:34816
	ds_read_b128 v[196:199], v157 offset:35840
	ds_read_b128 v[200:203], v157 offset:36864
	ds_read_b128 v[204:207], v157 offset:37888
	ds_read_b128 v[208:211], v157 offset:38912
	ds_read_b128 v[212:215], v157 offset:39936
	global_load_lds_dwordx4 v128, s[98:99]
	s_mov_b32 m0, s90
	s_add_u32 s58, s52, 0x80080
	s_addc_u32 s59, s53, 0
	global_load_lds_dwordx4 v132, s[98:99]
	s_add_u32 s98, s54, 0x80
	s_addc_u32 s99, s55, 0
	s_waitcnt vmcnt(8)
	s_waitcnt lgkmcnt(0)
	s_barrier
	s_waitcnt lgkmcnt(0)
	v_mfma_f32_16x16x32_bf16 v[124:127], v[144:147], v[182:185], v[124:127]
	v_mfma_f32_16x16x32_bf16 v[120:123], v[158:161], v[182:185], v[120:123]
	v_mfma_f32_16x16x32_bf16 v[108:111], v[144:147], v[192:195], v[108:111]
	v_mfma_f32_16x16x32_bf16 v[104:107], v[158:161], v[192:195], v[104:107]
	v_mfma_f32_16x16x32_bf16 v[92:95], v[144:147], v[200:203], v[92:95]
	v_mfma_f32_16x16x32_bf16 v[88:91], v[158:161], v[200:203], v[88:91]
	v_mfma_f32_16x16x32_bf16 v[76:79], v[144:147], v[208:211], v[76:79]
	v_mfma_f32_16x16x32_bf16 v[72:75], v[158:161], v[208:211], v[72:75]
	v_mfma_f32_16x16x32_bf16 v[124:127], v[148:151], v[188:191], v[124:127]
	v_mfma_f32_16x16x32_bf16 v[120:123], v[162:165], v[188:191], v[120:123]
	v_mfma_f32_16x16x32_bf16 v[108:111], v[148:151], v[196:199], v[108:111]
	v_mfma_f32_16x16x32_bf16 v[104:107], v[162:165], v[196:199], v[104:107]
	v_mfma_f32_16x16x32_bf16 v[92:95], v[148:151], v[204:207], v[92:95]
	v_mfma_f32_16x16x32_bf16 v[88:91], v[162:165], v[204:207], v[88:91]
	v_mfma_f32_16x16x32_bf16 v[76:79], v[148:151], v[212:215], v[76:79]
	v_mfma_f32_16x16x32_bf16 v[72:75], v[162:165], v[212:215], v[72:75]
	v_mfma_f32_16x16x32_bf16 v[116:119], v[166:169], v[182:185], v[116:119]
	v_mfma_f32_16x16x32_bf16 v[112:115], v[174:177], v[182:185], v[112:115]
	v_mfma_f32_16x16x32_bf16 v[100:103], v[166:169], v[192:195], v[100:103]
	v_mfma_f32_16x16x32_bf16 v[96:99], v[174:177], v[192:195], v[96:99]
	v_mfma_f32_16x16x32_bf16 v[84:87], v[166:169], v[200:203], v[84:87]
	v_mfma_f32_16x16x32_bf16 v[80:83], v[174:177], v[200:203], v[80:83]
	v_mfma_f32_16x16x32_bf16 v[68:71], v[166:169], v[208:211], v[68:71]
	v_mfma_f32_16x16x32_bf16 v[64:67], v[174:177], v[208:211], v[64:67]
	v_mfma_f32_16x16x32_bf16 v[116:119], v[170:173], v[188:191], v[116:119]
	v_mfma_f32_16x16x32_bf16 v[112:115], v[178:181], v[188:191], v[112:115]
	v_mfma_f32_16x16x32_bf16 v[100:103], v[170:173], v[196:199], v[100:103]
	v_mfma_f32_16x16x32_bf16 v[96:99], v[178:181], v[196:199], v[96:99]
	v_mfma_f32_16x16x32_bf16 v[84:87], v[170:173], v[204:207], v[84:87]
	v_mfma_f32_16x16x32_bf16 v[80:83], v[178:181], v[204:207], v[80:83]
	v_mfma_f32_16x16x32_bf16 v[68:71], v[170:173], v[212:215], v[68:71]
	v_mfma_f32_16x16x32_bf16 v[64:67], v[178:181], v[212:215], v[64:67]
	s_barrier
	s_mov_b32 m0, s27
	s_nop 0
	ds_read_b128 v[182:185], v157 offset:49152
	ds_read_b128 v[188:191], v157 offset:50176
	ds_read_b128 v[192:195], v157 offset:51200
	ds_read_b128 v[196:199], v157 offset:52224
	ds_read_b128 v[200:203], v157 offset:53248
	ds_read_b128 v[204:207], v157 offset:54272
	ds_read_b128 v[208:211], v157 offset:55296
	ds_read_b128 v[212:215], v157 offset:56320
	global_load_lds_dwordx4 v130, s[100:101]
	s_mov_b32 m0, s34
	s_nop 0
	global_load_lds_dwordx4 v134, s[100:101]
	s_mov_b32 m0, s35
	s_nop 0
	global_load_lds_dwordx4 v130, s[58:59]
	s_mov_b32 m0, s28
	s_nop 0
	global_load_lds_dwordx4 v134, s[58:59]
	s_mov_b32 m0, s92
	s_nop 0
	global_load_lds_dwordx4 v128, s[98:99]
	s_mov_b32 m0, s93
	s_nop 0
	global_load_lds_dwordx4 v132, s[98:99]
	s_waitcnt vmcnt(8)
	s_waitcnt lgkmcnt(0)
	s_barrier
	s_waitcnt lgkmcnt(0)
	v_mfma_f32_16x16x32_bf16 v[60:63], v[144:147], v[182:185], v[60:63]
	v_mfma_f32_16x16x32_bf16 v[56:59], v[158:161], v[182:185], v[56:59]
	v_mfma_f32_16x16x32_bf16 v[44:47], v[144:147], v[192:195], v[44:47]
	v_mfma_f32_16x16x32_bf16 v[40:43], v[158:161], v[192:195], v[40:43]
	v_mfma_f32_16x16x32_bf16 v[28:31], v[144:147], v[200:203], v[28:31]
	v_mfma_f32_16x16x32_bf16 v[24:27], v[158:161], v[200:203], v[24:27]
	v_mfma_f32_16x16x32_bf16 v[12:15], v[144:147], v[208:211], v[12:15]
	v_mfma_f32_16x16x32_bf16 v[8:11], v[158:161], v[208:211], v[8:11]
	v_mfma_f32_16x16x32_bf16 v[60:63], v[148:151], v[188:191], v[60:63]
	v_mfma_f32_16x16x32_bf16 v[56:59], v[162:165], v[188:191], v[56:59]
	v_mfma_f32_16x16x32_bf16 v[44:47], v[148:151], v[196:199], v[44:47]
	v_mfma_f32_16x16x32_bf16 v[40:43], v[162:165], v[196:199], v[40:43]
	v_mfma_f32_16x16x32_bf16 v[28:31], v[148:151], v[204:207], v[28:31]
	v_mfma_f32_16x16x32_bf16 v[24:27], v[162:165], v[204:207], v[24:27]
	v_mfma_f32_16x16x32_bf16 v[12:15], v[148:151], v[212:215], v[12:15]
	v_mfma_f32_16x16x32_bf16 v[8:11], v[162:165], v[212:215], v[8:11]
	v_mfma_f32_16x16x32_bf16 v[52:55], v[166:169], v[182:185], v[52:55]
	v_mfma_f32_16x16x32_bf16 v[48:51], v[174:177], v[182:185], v[48:51]
	v_mfma_f32_16x16x32_bf16 v[36:39], v[166:169], v[192:195], v[36:39]
	v_mfma_f32_16x16x32_bf16 v[32:35], v[174:177], v[192:195], v[32:35]
	v_mfma_f32_16x16x32_bf16 v[20:23], v[166:169], v[200:203], v[20:23]
	v_mfma_f32_16x16x32_bf16 v[16:19], v[174:177], v[200:203], v[16:19]
	v_mfma_f32_16x16x32_bf16 v[4:7], v[166:169], v[208:211], v[4:7]
	v_mfma_f32_16x16x32_bf16 v[0:3], v[174:177], v[208:211], v[0:3]
	v_mfma_f32_16x16x32_bf16 v[52:55], v[170:173], v[188:191], v[52:55]
	v_mfma_f32_16x16x32_bf16 v[48:51], v[178:181], v[188:191], v[48:51]
	v_mfma_f32_16x16x32_bf16 v[36:39], v[170:173], v[196:199], v[36:39]
	v_mfma_f32_16x16x32_bf16 v[32:35], v[178:181], v[196:199], v[32:35]
	v_mfma_f32_16x16x32_bf16 v[20:23], v[170:173], v[204:207], v[20:23]
	v_mfma_f32_16x16x32_bf16 v[16:19], v[178:181], v[204:207], v[16:19]
	v_mfma_f32_16x16x32_bf16 v[4:7], v[170:173], v[212:215], v[4:7]
	v_mfma_f32_16x16x32_bf16 v[0:3], v[178:181], v[212:215], v[0:3]
	s_barrier
	s_add_i32 s45, s45, 2
	s_add_u32 s50, s50, 0x100
	s_addc_u32 s51, s51, 0
	s_add_u32 s23, s23, 0x100
	s_addc_u32 s25, s25, 0
	s_cmp_gt_u32 s45, 29
	s_cbranch_scc0 .LBB0_413
	s_setprio 0
	s_and_b64 vcc, exec, s[78:79]
	s_cbranch_vccz .LBB0_416
	s_barrier
